# plus Hyena gating: the two late neighbour-sample loads issued with the first load batch
# speedup vs baseline: 1.0080x; 1.0019x over previous
.LBB0_728:
	s_or_b64 exec, exec, s[4:5]
	s_lshl_b32 s36, s21, 9
	s_lshl_b64 s[4:5], s[36:37], 2
	s_add_u32 s6, s40, s4
	s_addc_u32 s7, s41, s5
	s_add_u32 s4, s68, s4
	s_addc_u32 s5, s69, s5
	s_waitcnt lgkmcnt(0)
	s_barrier
	global_load_dword v76, v145, s[6:7] offset:2048
	global_load_dword v74, v175, s[6:7]
	global_load_dword v72, v174, s[6:7] offset:2048
	global_load_dword v78, v145, s[4:5] offset:2048
	s_add_i32 s4, s36, s38
	s_ashr_i32 s5, s4, 31
	s_lshl_b64 s[4:5], s[4:5], 2
	s_add_u32 s4, s76, s4
	s_addc_u32 s5, s77, s5
	global_load_dword v80, v145, s[4:5]
	s_add_i32 s4, s36, s93
	s_ashr_i32 s5, s4, 31
	s_lshl_b64 s[4:5], s[4:5], 17
	s_add_u32 s4, s30, s4
	s_addc_u32 s5, s31, s5
	s_add_u32 s6, s4, s19
	s_addc_u32 s7, s5, 0
	s_add_u32 s4, s4, s20
	s_addc_u32 s5, s5, 0
	v_lshl_add_u64 v[0:1], s[6:7], 0, v[28:29]
	global_load_dwordx4 v[86:89], v[0:1], off
	v_lshl_add_u64 v[84:85], v[0:1], 0, v[24:25]
	v_lshl_add_u64 v[82:83], v[0:1], 0, v[144:145]
	v_lshl_add_u64 v[0:1], s[4:5], 0, v[28:29]
	v_lshl_add_u64 v[106:107], v[0:1], 0, v[24:25]
	global_load_dwordx4 v[90:93], v[0:1], off
	v_lshl_add_u64 v[108:109], v[0:1], 0, v[144:145]
	ds_read2_b64 v[94:97], v121 offset1:1
	ds_read2_b64 v[98:101], v121 offset0:2 offset1:3
	ds_read2_b64 v[102:105], v121 offset0:4 offset1:5
	ds_read2_b64 v[0:3], v121 offset0:6 offset1:7
	global_load_ushort v23, v[106:107], off
	global_load_ushort v73, v[84:85], off
	global_load_ushort v222, v[108:109], off
	global_load_ushort v223, v[82:83], off
	s_andn2_b64 vcc, exec, s[70:71]
	s_waitcnt vmcnt(6) lgkmcnt(3)
	v_pk_fma_f32 v[46:47], v[46:47], v[80:81], v[94:95] op_sel_hi:[1,0,1]
	s_waitcnt lgkmcnt(2)
	v_pk_fma_f32 v[34:35], v[34:35], v[80:81], v[98:99] op_sel_hi:[1,0,1]
	v_pk_fma_f32 v[36:37], v[36:37], v[80:81], v[100:101] op_sel_hi:[1,0,1]
	v_pk_fma_f32 v[32:33], v[32:33], v[80:81], v[96:97] op_sel_hi:[1,0,1]
	s_waitcnt lgkmcnt(1)
	v_pk_fma_f32 v[38:39], v[38:39], v[80:81], v[102:103] op_sel_hi:[1,0,1]
	v_pk_fma_f32 v[40:41], v[40:41], v[80:81], v[104:105] op_sel_hi:[1,0,1]
	s_waitcnt lgkmcnt(0)
	v_pk_fma_f32 v[0:1], v[42:43], v[80:81], v[0:1] op_sel_hi:[1,0,1]
	v_pk_fma_f32 v[2:3], v[44:45], v[80:81], v[2:3] op_sel_hi:[1,0,1]
	s_waitcnt vmcnt(5)
	v_lshlrev_b32_e32 v110, 16, v86
	v_and_b32_e32 v112, 0xffff0000, v86
	s_waitcnt vmcnt(4)
	v_lshlrev_b32_e32 v111, 16, v90
	v_and_b32_e32 v113, 0xffff0000, v90
	s_waitcnt vmcnt(3)
	v_lshlrev_b32_e32 v23, 16, v23
	s_waitcnt vmcnt(2)
	v_lshlrev_b32_e32 v73, 16, v73
	v_cndmask_b32_e64 v85, 0, v23, s[46:47]
	v_cndmask_b32_e64 v84, 0, v73, s[46:47]
	v_pk_fma_f32 v[84:85], v[76:77], v[84:85], v[78:79] op_sel_hi:[0,1,0]
	v_pk_fma_f32 v[84:85], v[74:75], v[110:111], v[84:85] op_sel_hi:[0,1,1]
	v_pk_fma_f32 v[84:85], v[72:73], v[112:113], v[84:85] op_sel_hi:[0,1,1]
	v_pk_mul_f32 v[46:47], v[46:47], v[84:85]
	v_lshlrev_b32_e32 v85, 16, v91
	v_lshlrev_b32_e32 v84, 16, v87
	v_pk_fma_f32 v[94:95], v[76:77], v[110:111], v[78:79] op_sel_hi:[0,1,0]
	v_and_b32_e32 v90, 0xffff0000, v87
	v_pk_fma_f32 v[86:87], v[76:77], v[112:113], v[78:79] op_sel_hi:[0,1,0]
	v_pk_fma_f32 v[94:95], v[74:75], v[112:113], v[94:95] op_sel_hi:[0,1,1]
	v_and_b32_e32 v91, 0xffff0000, v91
	v_pk_fma_f32 v[86:87], v[74:75], v[84:85], v[86:87] op_sel_hi:[0,1,1]
	v_pk_fma_f32 v[94:95], v[72:73], v[84:85], v[94:95] op_sel_hi:[0,1,1]
	v_pk_fma_f32 v[86:87], v[72:73], v[90:91], v[86:87] op_sel_hi:[0,1,1]
	v_pk_fma_f32 v[84:85], v[76:77], v[84:85], v[78:79] op_sel_hi:[0,1,0]
	v_pk_mul_f32 v[34:35], v[86:87], v[34:35]
	v_lshlrev_b32_e32 v87, 16, v92
	v_lshlrev_b32_e32 v86, 16, v88
	v_pk_fma_f32 v[84:85], v[74:75], v[90:91], v[84:85] op_sel_hi:[0,1,1]
	v_pk_fma_f32 v[84:85], v[72:73], v[86:87], v[84:85] op_sel_hi:[0,1,1]
	v_pk_mul_f32 v[36:37], v[84:85], v[36:37]
	v_pk_fma_f32 v[84:85], v[76:77], v[90:91], v[78:79] op_sel_hi:[0,1,0]
	v_pk_mul_f32 v[32:33], v[32:33], v[94:95]
	v_and_b32_e32 v95, 0xffff0000, v92
	v_and_b32_e32 v94, 0xffff0000, v88
	v_pk_fma_f32 v[84:85], v[74:75], v[86:87], v[84:85] op_sel_hi:[0,1,1]
	v_pk_fma_f32 v[84:85], v[72:73], v[94:95], v[84:85] op_sel_hi:[0,1,1]
	v_pk_fma_f32 v[86:87], v[76:77], v[86:87], v[78:79] op_sel_hi:[0,1,0]
	v_pk_mul_f32 v[38:39], v[84:85], v[38:39]
	v_lshlrev_b32_e32 v85, 16, v93
	v_lshlrev_b32_e32 v84, 16, v89
	v_pk_fma_f32 v[86:87], v[74:75], v[94:95], v[86:87] op_sel_hi:[0,1,1]
	v_pk_fma_f32 v[86:87], v[72:73], v[84:85], v[86:87] op_sel_hi:[0,1,1]
	v_pk_mul_f32 v[40:41], v[86:87], v[40:41]
	v_and_b32_e32 v86, 0xffff0000, v89
	v_pk_fma_f32 v[88:89], v[76:77], v[94:95], v[78:79] op_sel_hi:[0,1,0]
	v_and_b32_e32 v87, 0xffff0000, v93
	v_pk_fma_f32 v[88:89], v[74:75], v[84:85], v[88:89] op_sel_hi:[0,1,1]
	v_pk_fma_f32 v[88:89], v[72:73], v[86:87], v[88:89] op_sel_hi:[0,1,1]
	v_pk_mul_f32 v[42:43], v[88:89], v[0:1]
	v_pk_fma_f32 v[82:83], v[76:77], v[84:85], v[78:79] op_sel_hi:[0,1,0]
	v_pk_fma_f32 v[82:83], v[74:75], v[86:87], v[82:83] op_sel_hi:[0,1,1]
	s_waitcnt vmcnt(1)
	v_lshlrev_b32_e32 v0, 16, v222
	s_waitcnt vmcnt(0)
	v_lshlrev_b32_e32 v23, 16, v223
	v_cndmask_b32_e64 v1, 0, v0, s[48:49]
	v_cndmask_b32_e64 v0, 0, v23, s[48:49]
	v_pk_fma_f32 v[0:1], v[72:73], v[0:1], v[82:83] op_sel_hi:[0,1,1]
	v_pk_mul_f32 v[44:45], v[0:1], v[2:3]
	v_lshl_add_u64 v[0:1], s[6:7], 0, v[30:31]
	v_mov_b32_e32 v23, v145
	global_load_dwordx4 v[88:91], v[0:1], off
	v_lshl_add_u64 v[104:105], v[0:1], 0, v[26:27]
	v_lshl_add_u64 v[86:87], v[0:1], 0, v[22:23]
	v_lshl_add_u64 v[0:1], s[4:5], 0, v[30:31]
	v_lshl_add_u64 v[106:107], v[0:1], 0, v[26:27]
	global_load_dwordx4 v[82:85], v[0:1], off
	v_lshl_add_u64 v[108:109], v[0:1], 0, v[22:23]
	ds_read2_b64 v[92:95], v125 offset1:1
	ds_read2_b64 v[96:99], v126 offset1:1
	ds_read2_b64 v[100:103], v127 offset1:1
	ds_read2_b64 v[0:3], v128 offset1:1
	global_load_ushort v23, v[106:107], off
	global_load_ushort v73, v[104:105], off
	global_load_ushort v224, v[108:109], off
	global_load_ushort v225, v[86:87], off
	s_waitcnt lgkmcnt(3)
	v_pk_fma_f32 v[48:49], v[48:49], v[80:81], v[92:93] op_sel_hi:[1,0,1]
	s_waitcnt lgkmcnt(2)
	v_pk_fma_f32 v[52:53], v[52:53], v[80:81], v[96:97] op_sel_hi:[1,0,1]
	v_pk_fma_f32 v[54:55], v[54:55], v[80:81], v[98:99] op_sel_hi:[1,0,1]
	s_waitcnt lgkmcnt(1)
	v_pk_fma_f32 v[56:57], v[56:57], v[80:81], v[100:101] op_sel_hi:[1,0,1]
	v_pk_fma_f32 v[58:59], v[58:59], v[80:81], v[102:103] op_sel_hi:[1,0,1]
	s_waitcnt lgkmcnt(0)
	v_pk_fma_f32 v[0:1], v[60:61], v[80:81], v[0:1] op_sel_hi:[1,0,1]
	v_pk_fma_f32 v[50:51], v[50:51], v[80:81], v[94:95] op_sel_hi:[1,0,1]
	v_pk_fma_f32 v[2:3], v[62:63], v[80:81], v[2:3] op_sel_hi:[1,0,1]
	s_mov_b64 s[4:5], -1
	s_waitcnt vmcnt(5)
	v_lshlrev_b32_e32 v110, 16, v88
	v_and_b32_e32 v112, 0xffff0000, v88
	v_lshlrev_b32_e32 v92, 16, v89
	s_waitcnt vmcnt(4)
	v_lshlrev_b32_e32 v111, 16, v82
	v_and_b32_e32 v113, 0xffff0000, v82
	s_waitcnt vmcnt(3)
	v_lshlrev_b32_e32 v23, 16, v23
	s_waitcnt vmcnt(2)
	v_lshlrev_b32_e32 v73, 16, v73
	v_cndmask_b32_e64 v105, 0, v23, s[50:51]
	v_cndmask_b32_e64 v104, 0, v73, s[50:51]
	v_pk_fma_f32 v[104:105], v[76:77], v[104:105], v[78:79] op_sel_hi:[0,1,0]
	v_pk_fma_f32 v[104:105], v[74:75], v[110:111], v[104:105] op_sel_hi:[0,1,1]
	v_pk_fma_f32 v[104:105], v[72:73], v[112:113], v[104:105] op_sel_hi:[0,1,1]
	v_pk_mul_f32 v[48:49], v[48:49], v[104:105]
	v_lshlrev_b32_e32 v93, 16, v83
	v_pk_fma_f32 v[104:105], v[76:77], v[110:111], v[78:79] op_sel_hi:[0,1,0]
	v_and_b32_e32 v82, 0xffff0000, v89
	v_pk_fma_f32 v[88:89], v[76:77], v[112:113], v[78:79] op_sel_hi:[0,1,0]
	v_pk_fma_f32 v[104:105], v[74:75], v[112:113], v[104:105] op_sel_hi:[0,1,1]
	v_and_b32_e32 v83, 0xffff0000, v83
	v_pk_fma_f32 v[88:89], v[74:75], v[92:93], v[88:89] op_sel_hi:[0,1,1]
	v_pk_fma_f32 v[104:105], v[72:73], v[92:93], v[104:105] op_sel_hi:[0,1,1]
	v_pk_fma_f32 v[88:89], v[72:73], v[82:83], v[88:89] op_sel_hi:[0,1,1]
	v_pk_fma_f32 v[92:93], v[76:77], v[92:93], v[78:79] op_sel_hi:[0,1,0]
	v_pk_mul_f32 v[52:53], v[88:89], v[52:53]
	v_lshlrev_b32_e32 v89, 16, v84
	v_lshlrev_b32_e32 v88, 16, v90
	v_pk_fma_f32 v[92:93], v[74:75], v[82:83], v[92:93] op_sel_hi:[0,1,1]
	v_pk_fma_f32 v[92:93], v[72:73], v[88:89], v[92:93] op_sel_hi:[0,1,1]
	v_pk_fma_f32 v[82:83], v[76:77], v[82:83], v[78:79] op_sel_hi:[0,1,0]
	v_pk_mul_f32 v[54:55], v[92:93], v[54:55]
	v_and_b32_e32 v93, 0xffff0000, v84
	v_and_b32_e32 v92, 0xffff0000, v90
	v_pk_fma_f32 v[82:83], v[74:75], v[88:89], v[82:83] op_sel_hi:[0,1,1]
	v_pk_fma_f32 v[82:83], v[72:73], v[92:93], v[82:83] op_sel_hi:[0,1,1]
	v_pk_fma_f32 v[88:89], v[76:77], v[88:89], v[78:79] op_sel_hi:[0,1,0]
	v_pk_mul_f32 v[56:57], v[82:83], v[56:57]
	v_lshlrev_b32_e32 v83, 16, v85
	v_lshlrev_b32_e32 v82, 16, v91
	v_pk_fma_f32 v[88:89], v[74:75], v[92:93], v[88:89] op_sel_hi:[0,1,1]
	v_pk_fma_f32 v[88:89], v[72:73], v[82:83], v[88:89] op_sel_hi:[0,1,1]
	v_pk_mul_f32 v[58:59], v[88:89], v[58:59]
	v_pk_fma_f32 v[88:89], v[76:77], v[92:93], v[78:79] op_sel_hi:[0,1,0]
	v_and_b32_e32 v85, 0xffff0000, v85
	v_and_b32_e32 v84, 0xffff0000, v91
	v_pk_fma_f32 v[88:89], v[74:75], v[82:83], v[88:89] op_sel_hi:[0,1,1]
	v_pk_fma_f32 v[88:89], v[72:73], v[84:85], v[88:89] op_sel_hi:[0,1,1]
	v_pk_mul_f32 v[60:61], v[88:89], v[0:1]
	v_pk_fma_f32 v[76:77], v[76:77], v[82:83], v[78:79] op_sel_hi:[0,1,0]
	v_pk_fma_f32 v[74:75], v[74:75], v[84:85], v[76:77] op_sel_hi:[0,1,1]
	v_pk_mul_f32 v[50:51], v[50:51], v[104:105]
	s_waitcnt vmcnt(1)
	v_lshlrev_b32_e32 v0, 16, v224
	s_waitcnt vmcnt(0)
	v_lshlrev_b32_e32 v23, 16, v225
	v_cndmask_b32_e64 v1, 0, v0, s[52:53]
	v_cndmask_b32_e64 v0, 0, v23, s[52:53]
	v_pk_fma_f32 v[0:1], v[72:73], v[0:1], v[74:75] op_sel_hi:[0,1,1]
	v_pk_mul_f32 v[62:63], v[0:1], v[2:3]
	s_cbranch_vccz .LBB0_730
	s_andn2_b64 vcc, exec, s[4:5]
	s_cbranch_vccnz .LBB0_667
	s_branch .LBB0_731

.LBB0_802:
	s_or_b64 exec, exec, s[4:5]
	s_lshl_b32 s36, s58, 9
	s_lshl_b64 s[4:5], s[36:37], 2
	s_add_u32 s6, s40, s4
	s_addc_u32 s7, s41, s5
	s_add_u32 s4, s54, s4
	s_addc_u32 s5, s55, s5
	s_waitcnt lgkmcnt(0)
	s_barrier
	global_load_dword v10, v145, s[6:7] offset:2048
	global_load_dword v8, v175, s[6:7]
	global_load_dword v6, v174, s[6:7] offset:2048
	global_load_dword v12, v145, s[4:5] offset:2048
	s_add_i32 s4, s36, s38
	s_ashr_i32 s5, s4, 31
	s_lshl_b64 s[4:5], s[4:5], 2
	s_add_u32 s4, s76, s4
	s_addc_u32 s5, s77, s5
	global_load_dword v4, v145, s[4:5]
	s_add_i32 s4, s36, s20
	s_ashr_i32 s5, s4, 31
	s_lshl_b64 s[4:5], s[4:5], 17
	s_add_u32 s6, s30, s4
	s_addc_u32 s7, s31, s5
	s_add_u32 s4, s6, s21
	s_addc_u32 s5, s7, 0
	v_lshl_add_u64 v[0:1], s[4:5], 0, v[40:41]
	s_add_u32 s4, s6, s39
	s_addc_u32 s5, s7, 0
	global_load_dwordx4 v[20:23], v[0:1], off
	v_lshl_add_u64 v[74:75], v[0:1], 0, v[48:49]
	v_lshl_add_u64 v[18:19], v[0:1], 0, v[144:145]
	v_lshl_add_u64 v[0:1], s[4:5], 0, v[40:41]
	v_lshl_add_u64 v[76:77], v[0:1], 0, v[48:49]
	global_load_dwordx4 v[24:27], v[0:1], off
	v_lshl_add_u64 v[78:79], v[0:1], 0, v[144:145]
	ds_read2_b64 v[14:17], v92 offset1:1
	ds_read2_b64 v[28:31], v92 offset0:2 offset1:3
	ds_read2_b64 v[70:73], v92 offset0:4 offset1:5
	ds_read2_b64 v[0:3], v92 offset0:6 offset1:7
	global_load_ushort v5, v[76:77], off
	global_load_ushort v7, v[74:75], off
	global_load_ushort v220, v[78:79], off
	global_load_ushort v221, v[18:19], off
	s_mov_b64 s[4:5], -1
	s_andn2_b64 vcc, exec, s[56:57]
	s_waitcnt vmcnt(5)
	v_lshlrev_b32_e32 v80, 16, v20
	v_and_b32_e32 v82, 0xffff0000, v20
	s_waitcnt vmcnt(4)
	v_lshlrev_b32_e32 v81, 16, v24
	v_and_b32_e32 v83, 0xffff0000, v24
	s_waitcnt vmcnt(3)
	v_lshlrev_b32_e32 v5, 16, v5
	s_waitcnt vmcnt(2)
	v_lshlrev_b32_e32 v7, 16, v7
	v_cndmask_b32_e64 v75, 0, v5, s[46:47]
	v_cndmask_b32_e64 v74, 0, v7, s[46:47]
	v_pk_fma_f32 v[74:75], v[10:11], v[74:75], v[12:13] op_sel_hi:[0,1,0]
	v_pk_fma_f32 v[74:75], v[8:9], v[80:81], v[74:75] op_sel_hi:[0,1,1]
	v_pk_fma_f32 v[74:75], v[6:7], v[82:83], v[74:75] op_sel_hi:[0,1,1]
	s_waitcnt lgkmcnt(3)
	v_pk_fma_f32 v[14:15], v[50:51], v[4:5], v[14:15] op_sel_hi:[1,0,1]
	v_pk_fma_f32 v[16:17], v[52:53], v[4:5], v[16:17] op_sel_hi:[1,0,1]
	v_pk_mul_f32 v[50:51], v[14:15], v[74:75]
	v_pk_fma_f32 v[74:75], v[10:11], v[80:81], v[12:13] op_sel_hi:[0,1,0]
	v_lshlrev_b32_e32 v15, 16, v25
	v_lshlrev_b32_e32 v14, 16, v21
	v_pk_fma_f32 v[74:75], v[8:9], v[82:83], v[74:75] op_sel_hi:[0,1,1]
	v_pk_fma_f32 v[74:75], v[6:7], v[14:15], v[74:75] op_sel_hi:[0,1,1]
	v_pk_mul_f32 v[52:53], v[16:17], v[74:75]
	v_and_b32_e32 v16, 0xffff0000, v21
	v_pk_fma_f32 v[20:21], v[10:11], v[82:83], v[12:13] op_sel_hi:[0,1,0]
	v_and_b32_e32 v17, 0xffff0000, v25
	v_pk_fma_f32 v[20:21], v[8:9], v[14:15], v[20:21] op_sel_hi:[0,1,1]
	v_pk_fma_f32 v[20:21], v[6:7], v[16:17], v[20:21] op_sel_hi:[0,1,1]
	s_waitcnt lgkmcnt(2)
	v_pk_fma_f32 v[24:25], v[54:55], v[4:5], v[28:29] op_sel_hi:[1,0,1]
	v_pk_fma_f32 v[14:15], v[10:11], v[14:15], v[12:13] op_sel_hi:[0,1,0]
	v_pk_mul_f32 v[54:55], v[20:21], v[24:25]
	v_lshlrev_b32_e32 v21, 16, v26
	v_lshlrev_b32_e32 v20, 16, v22
	v_pk_fma_f32 v[14:15], v[8:9], v[16:17], v[14:15] op_sel_hi:[0,1,1]
	v_pk_fma_f32 v[14:15], v[6:7], v[20:21], v[14:15] op_sel_hi:[0,1,1]
	v_pk_fma_f32 v[24:25], v[56:57], v[4:5], v[30:31] op_sel_hi:[1,0,1]
	s_waitcnt lgkmcnt(0)
	v_pk_fma_f32 v[0:1], v[62:63], v[4:5], v[0:1] op_sel_hi:[1,0,1]
	v_pk_mul_f32 v[56:57], v[14:15], v[24:25]
	v_pk_fma_f32 v[14:15], v[10:11], v[16:17], v[12:13] op_sel_hi:[0,1,0]
	v_and_b32_e32 v25, 0xffff0000, v26
	v_and_b32_e32 v24, 0xffff0000, v22
	v_pk_fma_f32 v[14:15], v[8:9], v[20:21], v[14:15] op_sel_hi:[0,1,1]
	v_pk_fma_f32 v[14:15], v[6:7], v[24:25], v[14:15] op_sel_hi:[0,1,1]
	v_pk_fma_f32 v[16:17], v[58:59], v[4:5], v[70:71] op_sel_hi:[1,0,1]
	s_nop 0
	v_pk_mul_f32 v[58:59], v[14:15], v[16:17]
	v_pk_fma_f32 v[14:15], v[10:11], v[20:21], v[12:13] op_sel_hi:[0,1,0]
	v_lshlrev_b32_e32 v17, 16, v27
	v_lshlrev_b32_e32 v16, 16, v23
	v_pk_fma_f32 v[14:15], v[8:9], v[24:25], v[14:15] op_sel_hi:[0,1,1]
	v_pk_fma_f32 v[14:15], v[6:7], v[16:17], v[14:15] op_sel_hi:[0,1,1]
	v_pk_fma_f32 v[20:21], v[60:61], v[4:5], v[72:73] op_sel_hi:[1,0,1]
	s_nop 0
	v_pk_mul_f32 v[60:61], v[14:15], v[20:21]
	v_pk_fma_f32 v[20:21], v[10:11], v[24:25], v[12:13] op_sel_hi:[0,1,0]
	v_and_b32_e32 v15, 0xffff0000, v27
	v_and_b32_e32 v14, 0xffff0000, v23
	v_pk_fma_f32 v[20:21], v[8:9], v[16:17], v[20:21] op_sel_hi:[0,1,1]
	v_pk_fma_f32 v[20:21], v[6:7], v[14:15], v[20:21] op_sel_hi:[0,1,1]
	v_pk_mul_f32 v[62:63], v[20:21], v[0:1]
	v_pk_fma_f32 v[10:11], v[10:11], v[16:17], v[12:13] op_sel_hi:[0,1,0]
	v_pk_fma_f32 v[8:9], v[8:9], v[14:15], v[10:11] op_sel_hi:[0,1,1]
	s_waitcnt vmcnt(1)
	v_lshlrev_b32_e32 v0, 16, v220
	s_waitcnt vmcnt(0)
	v_lshlrev_b32_e32 v5, 16, v221
	v_cndmask_b32_e64 v1, 0, v0, s[48:49]
	v_cndmask_b32_e64 v0, 0, v5, s[48:49]
	v_pk_fma_f32 v[0:1], v[6:7], v[0:1], v[8:9] op_sel_hi:[0,1,1]
	v_pk_fma_f32 v[2:3], v[64:65], v[4:5], v[2:3] op_sel_hi:[1,0,1]
	s_nop 0
	v_pk_mul_f32 v[64:65], v[0:1], v[2:3]
	s_cbranch_vccz .LBB0_804
	s_andn2_b64 vcc, exec, s[4:5]
	s_cbranch_vccnz .LBB0_759
	s_branch .LBB0_805
